# v14 with the second attention loop shifted by 4 bytes (code placement: loop body now 0 mod 8)
# speedup vs baseline: 1.0020x; 1.0020x over previous
.LBB0_571:
	s_or_b64 exec, exec, s[8:9]
	v_mov_b32_e32 v0, v1
	s_waitcnt vmcnt(0) lgkmcnt(0)
	s_barrier
	s_lshl_b32 s8, s43, 8
	v_mbcnt_lo_u32_b32 v0, -1, v0
	v_mbcnt_hi_u32_b32 v0, -1, v0
	v_add_u32_e32 v98, s54, v0
	v_mov_b64_e32 v[2:3], s[70:71]
	v_readfirstlane_b32 s9, v98
	s_ashr_i32 s0, s9, 6
	s_lshl_b32 s6, s0, 5
	v_and_b32_e32 v238, 31, v98
	s_add_i32 s20, s6, s8
	v_or_b32_e32 v34, s20, v238
	v_bfe_u32 v237, v98, 5, 1
	v_mad_i64_i32 v[2:3], s[10:11], v34, s46, v[2:3]
	s_lshl_b32 s86, s45, 1
	v_lshl_add_u64 v[2:3], v[2:3], 0, s[86:87]
	v_lshlrev_b32_e32 v0, 4, v237
	v_lshl_add_u64 v[2:3], v[2:3], 0, v[0:1]
	global_load_dwordx4 v[38:41], v[2:3], off
	global_load_dwordx4 v[46:49], v[2:3], off offset:32
	global_load_dwordx4 v[54:57], v[2:3], off offset:64
	global_load_dwordx4 v[62:65], v[2:3], off offset:96
	global_load_dwordx4 v[30:33], v[2:3], off offset:128
	global_load_dwordx4 v[26:29], v[2:3], off offset:160
	global_load_dwordx4 v[22:25], v[2:3], off offset:192
	global_load_dwordx4 v[18:21], v[2:3], off offset:224
	global_load_dwordx4 v[14:17], v[2:3], off offset:256
	global_load_dwordx4 v[6:9], v[2:3], off offset:288
	global_load_dwordx4 v[10:13], v[2:3], off offset:320
	s_nop 0
	global_load_dwordx4 v[2:5], v[2:3], off offset:352
	v_ashrrev_i32_e32 v35, 31, v34
	v_lshl_add_u64 v[34:35], v[34:35], 2, s[68:69]
	global_load_dword v239, v[34:35], off
	s_lshl_b32 s7, s0, 2
	v_bfe_u32 v102, v98, 3, 1
	v_mov_b64_e32 v[100:101], s[66:67]
	s_lshl_b32 s0, s0, 10
	s_add_i32 s0, s0, 0
	s_mov_b32 m0, s0
	s_waitcnt vmcnt(12)
	v_lshlrev_b32_e32 v118, 16, v38
	v_and_b32_e32 v119, 0xffff0000, v38
	v_lshlrev_b32_e32 v120, 16, v39
	v_and_b32_e32 v121, 0xffff0000, v39
	v_pk_mul_f32 v[34:35], v[118:119], v[118:119]
	v_pk_mul_f32 v[36:37], v[120:121], v[120:121]
	v_lshlrev_b32_e32 v122, 16, v40
	v_and_b32_e32 v123, 0xffff0000, v40
	v_pk_mul_f32 v[38:39], v[122:123], v[122:123]
	v_lshlrev_b32_e32 v124, 16, v41
	v_and_b32_e32 v125, 0xffff0000, v41
	v_add_f32_e32 v36, v36, v37
	v_add_f32_e32 v34, v34, v35
	v_pk_mul_f32 v[40:41], v[124:125], v[124:125]
	s_waitcnt vmcnt(11)
	v_lshlrev_b32_e32 v114, 16, v46
	v_and_b32_e32 v115, 0xffff0000, v46
	v_add_f32_e32 v34, v34, v36
	v_add_f32_e32 v35, v38, v39
	v_pk_mul_f32 v[42:43], v[114:115], v[114:115]
	v_lshlrev_b32_e32 v116, 16, v47
	v_and_b32_e32 v117, 0xffff0000, v47
	v_add_f32_e32 v0, v40, v41
	v_add_f32_e32 v34, v35, v34
	v_pk_mul_f32 v[44:45], v[116:117], v[116:117]
	v_lshlrev_b32_e32 v126, 16, v48
	v_and_b32_e32 v127, 0xffff0000, v48
	v_add_f32_e32 v0, v0, v34
	v_add_f32_e32 v34, v42, v43
	v_pk_mul_f32 v[46:47], v[126:127], v[126:127]
	v_lshlrev_b32_e32 v128, 16, v49
	v_and_b32_e32 v129, 0xffff0000, v49
	v_add_f32_e32 v0, v34, v0
	v_add_f32_e32 v34, v44, v45
	v_pk_mul_f32 v[48:49], v[128:129], v[128:129]
	s_waitcnt vmcnt(10)
	v_lshlrev_b32_e32 v130, 16, v54
	v_and_b32_e32 v131, 0xffff0000, v54
	v_add_f32_e32 v0, v34, v0
	v_add_f32_e32 v34, v46, v47
	v_pk_mul_f32 v[50:51], v[130:131], v[130:131]
	v_lshlrev_b32_e32 v132, 16, v55
	v_and_b32_e32 v133, 0xffff0000, v55
	v_add_f32_e32 v0, v34, v0
	v_add_f32_e32 v34, v48, v49
	v_pk_mul_f32 v[52:53], v[132:133], v[132:133]
	v_lshlrev_b32_e32 v134, 16, v56
	v_and_b32_e32 v135, 0xffff0000, v56
	v_add_f32_e32 v0, v34, v0
	v_add_f32_e32 v34, v50, v51
	v_pk_mul_f32 v[54:55], v[134:135], v[134:135]
	v_lshlrev_b32_e32 v136, 16, v57
	v_and_b32_e32 v137, 0xffff0000, v57
	v_add_f32_e32 v0, v34, v0
	v_add_f32_e32 v34, v52, v53
	v_pk_mul_f32 v[56:57], v[136:137], v[136:137]
	s_waitcnt vmcnt(9)
	v_lshlrev_b32_e32 v138, 16, v62
	v_and_b32_e32 v139, 0xffff0000, v62
	v_add_f32_e32 v0, v34, v0
	v_add_f32_e32 v34, v54, v55
	v_pk_mul_f32 v[58:59], v[138:139], v[138:139]
	v_lshlrev_b32_e32 v140, 16, v63
	v_and_b32_e32 v141, 0xffff0000, v63
	v_add_f32_e32 v0, v34, v0
	v_add_f32_e32 v34, v56, v57
	v_pk_mul_f32 v[60:61], v[140:141], v[140:141]
	v_lshlrev_b32_e32 v142, 16, v64
	v_and_b32_e32 v143, 0xffff0000, v64
	v_add_f32_e32 v0, v34, v0
	v_add_f32_e32 v34, v58, v59
	v_pk_mul_f32 v[62:63], v[142:143], v[142:143]
	v_lshlrev_b32_e32 v144, 16, v65
	v_and_b32_e32 v145, 0xffff0000, v65
	v_add_f32_e32 v0, v34, v0
	v_add_f32_e32 v34, v60, v61
	v_pk_mul_f32 v[64:65], v[144:145], v[144:145]
	s_waitcnt vmcnt(8)
	v_lshlrev_b32_e32 v146, 16, v30
	v_and_b32_e32 v147, 0xffff0000, v30
	v_add_f32_e32 v0, v34, v0
	v_add_f32_e32 v34, v62, v63
	v_pk_mul_f32 v[66:67], v[146:147], v[146:147]
	v_lshlrev_b32_e32 v148, 16, v31
	v_and_b32_e32 v149, 0xffff0000, v31
	v_add_f32_e32 v0, v34, v0
	v_add_f32_e32 v34, v64, v65
	v_pk_mul_f32 v[30:31], v[148:149], v[148:149]
	v_lshlrev_b32_e32 v150, 16, v32
	v_and_b32_e32 v151, 0xffff0000, v32
	v_add_f32_e32 v0, v34, v0
	v_add_f32_e32 v34, v66, v67
	v_pk_mul_f32 v[68:69], v[150:151], v[150:151]
	v_lshlrev_b32_e32 v152, 16, v33
	v_and_b32_e32 v153, 0xffff0000, v33
	v_add_f32_e32 v0, v34, v0
	v_add_f32_e32 v30, v30, v31
	v_pk_mul_f32 v[32:33], v[152:153], v[152:153]
	s_waitcnt vmcnt(7)
	v_lshlrev_b32_e32 v154, 16, v26
	v_and_b32_e32 v155, 0xffff0000, v26
	v_add_f32_e32 v0, v30, v0
	v_add_f32_e32 v30, v68, v69
	v_pk_mul_f32 v[70:71], v[154:155], v[154:155]
	v_lshlrev_b32_e32 v160, 16, v27
	v_and_b32_e32 v161, 0xffff0000, v27
	v_add_f32_e32 v0, v30, v0
	v_add_f32_e32 v30, v32, v33
	v_pk_mul_f32 v[26:27], v[160:161], v[160:161]
	v_lshlrev_b32_e32 v158, 16, v28
	v_and_b32_e32 v159, 0xffff0000, v28
	v_add_f32_e32 v0, v30, v0
	v_add_f32_e32 v30, v70, v71
	v_pk_mul_f32 v[72:73], v[158:159], v[158:159]
	v_lshlrev_b32_e32 v156, 16, v29
	v_and_b32_e32 v157, 0xffff0000, v29
	v_add_f32_e32 v0, v30, v0
	v_add_f32_e32 v26, v26, v27
	v_pk_mul_f32 v[28:29], v[156:157], v[156:157]
	s_waitcnt vmcnt(6)
	v_lshlrev_b32_e32 v162, 16, v22
	v_and_b32_e32 v163, 0xffff0000, v22
	v_add_f32_e32 v0, v26, v0
	v_add_f32_e32 v26, v72, v73
	v_pk_mul_f32 v[74:75], v[162:163], v[162:163]
	v_lshlrev_b32_e32 v166, 16, v23
	v_and_b32_e32 v167, 0xffff0000, v23
	v_add_f32_e32 v0, v26, v0
	v_add_f32_e32 v26, v28, v29
	v_pk_mul_f32 v[22:23], v[166:167], v[166:167]
	v_lshlrev_b32_e32 v164, 16, v24
	v_and_b32_e32 v165, 0xffff0000, v24
	v_add_f32_e32 v0, v26, v0
	v_add_f32_e32 v26, v74, v75
	v_pk_mul_f32 v[76:77], v[164:165], v[164:165]
	v_lshlrev_b32_e32 v168, 16, v25
	v_and_b32_e32 v169, 0xffff0000, v25
	v_add_f32_e32 v0, v26, v0
	v_add_f32_e32 v22, v22, v23
	v_pk_mul_f32 v[24:25], v[168:169], v[168:169]
	s_waitcnt vmcnt(5)
	v_lshlrev_b32_e32 v170, 16, v18
	v_and_b32_e32 v171, 0xffff0000, v18
	v_add_f32_e32 v0, v22, v0
	v_add_f32_e32 v22, v76, v77
	v_pk_mul_f32 v[78:79], v[170:171], v[170:171]
	v_lshlrev_b32_e32 v172, 16, v19
	v_and_b32_e32 v173, 0xffff0000, v19
	v_add_f32_e32 v0, v22, v0
	v_add_f32_e32 v22, v24, v25
	v_pk_mul_f32 v[18:19], v[172:173], v[172:173]
	v_lshlrev_b32_e32 v182, 16, v20
	v_and_b32_e32 v183, 0xffff0000, v20
	v_add_f32_e32 v0, v22, v0
	v_add_f32_e32 v22, v78, v79
	v_pk_mul_f32 v[80:81], v[182:183], v[182:183]
	v_lshlrev_b32_e32 v184, 16, v21
	v_and_b32_e32 v185, 0xffff0000, v21
	v_add_f32_e32 v0, v22, v0
	v_add_f32_e32 v18, v18, v19
	v_pk_mul_f32 v[20:21], v[184:185], v[184:185]
	s_waitcnt vmcnt(4)
	v_lshlrev_b32_e32 v188, 16, v14
	v_and_b32_e32 v189, 0xffff0000, v14
	v_add_f32_e32 v0, v18, v0
	v_add_f32_e32 v18, v80, v81
	v_pk_mul_f32 v[82:83], v[188:189], v[188:189]
	v_lshlrev_b32_e32 v186, 16, v15
	v_and_b32_e32 v187, 0xffff0000, v15
	v_add_f32_e32 v0, v18, v0
	v_add_f32_e32 v18, v20, v21
	v_pk_mul_f32 v[14:15], v[186:187], v[186:187]
	v_lshlrev_b32_e32 v196, 16, v16
	v_and_b32_e32 v197, 0xffff0000, v16
	v_add_f32_e32 v0, v18, v0
	v_add_f32_e32 v18, v82, v83
	v_pk_mul_f32 v[84:85], v[196:197], v[196:197]
	v_lshlrev_b32_e32 v194, 16, v17
	v_and_b32_e32 v195, 0xffff0000, v17
	v_add_f32_e32 v0, v18, v0
	v_add_f32_e32 v14, v14, v15
	v_pk_mul_f32 v[16:17], v[194:195], v[194:195]
	s_waitcnt vmcnt(3)
	v_lshlrev_b32_e32 v202, 16, v6
	v_and_b32_e32 v203, 0xffff0000, v6
	v_add_f32_e32 v0, v14, v0
	v_add_f32_e32 v14, v84, v85
	s_waitcnt vmcnt(2)
	v_and_b32_e32 v193, 0xffff0000, v11
	v_pk_mul_f32 v[86:87], v[202:203], v[202:203]
	v_lshlrev_b32_e32 v206, 16, v7
	v_and_b32_e32 v207, 0xffff0000, v7
	v_and_b32_e32 v201, 0xffff0000, v9
	v_add_f32_e32 v0, v14, v0
	v_add_f32_e32 v14, v16, v17
	v_lshlrev_b32_e32 v192, 16, v10
	v_and_b32_e32 v215, 0xffff0000, v10
	v_mov_b32_e32 v214, v193
	v_pk_mul_f32 v[6:7], v[206:207], v[206:207]
	v_lshlrev_b32_e32 v212, 16, v8
	v_and_b32_e32 v223, 0xffff0000, v8
	v_mov_b32_e32 v222, v201
	v_add_f32_e32 v0, v14, v0
	v_add_f32_e32 v14, v86, v87
	v_lshlrev_b32_e32 v190, 16, v11
	v_mov_b32_e32 v191, v192
	v_pk_mul_f32 v[10:11], v[214:215], v[214:215]
	v_lshlrev_b32_e32 v220, 16, v9
	v_mov_b32_e32 v221, v212
	v_pk_mul_f32 v[8:9], v[222:223], v[222:223]
	v_add_f32_e32 v0, v14, v0
	v_add_f32_e32 v6, v6, v7
	v_pk_fma_f32 v[10:11], v[190:191], v[190:191], v[10:11]
	v_and_b32_e32 v191, 0xffff0000, v13
	v_pk_fma_f32 v[8:9], v[220:221], v[220:221], v[8:9]
	v_add_f32_e32 v0, v6, v0
	v_lshlrev_b32_e32 v200, 16, v12
	v_and_b32_e32 v217, 0xffff0000, v12
	v_mov_b32_e32 v216, v191
	v_add_f32_e32 v0, v9, v0
	v_lshlrev_b32_e32 v198, 16, v13
	v_mov_b32_e32 v199, v200
	v_pk_mul_f32 v[12:13], v[216:217], v[216:217]
	v_add_f32_e32 v0, v8, v0
	v_pk_fma_f32 v[12:13], v[198:199], v[198:199], v[12:13]
	s_waitcnt vmcnt(1)
	v_and_b32_e32 v199, 0xffff0000, v3
	v_add_f32_e32 v0, v11, v0
	v_lshlrev_b32_e32 v204, 16, v2
	v_and_b32_e32 v219, 0xffff0000, v2
	v_mov_b32_e32 v218, v199
	v_add_f32_e32 v0, v10, v0
	v_lshlrev_b32_e32 v208, 16, v3
	v_mov_b32_e32 v209, v204
	v_pk_mul_f32 v[2:3], v[218:219], v[218:219]
	v_and_b32_e32 v205, 0xffff0000, v5
	v_add_f32_e32 v0, v13, v0
	v_pk_fma_f32 v[2:3], v[208:209], v[208:209], v[2:3]
	v_lshlrev_b32_e32 v210, 16, v4
	v_and_b32_e32 v225, 0xffff0000, v4
	v_mov_b32_e32 v224, v205
	v_add_f32_e32 v0, v12, v0
	v_lshlrev_b32_e32 v226, 16, v5
	v_mov_b32_e32 v227, v210
	v_pk_mul_f32 v[4:5], v[224:225], v[224:225]
	v_add_f32_e32 v0, v3, v0
	v_pk_fma_f32 v[4:5], v[226:227], v[226:227], v[4:5]
	v_add_f32_e32 v0, v2, v0
	v_add_f32_e32 v0, v5, v0
	v_add_f32_e32 v209, v4, v0
	v_and_b32_e32 v0, 32, v98
	global_load_dwordx4 v[2:5], v0, s[24:25] offset:16
	global_load_dwordx4 v[14:17], v0, s[24:25]
	global_load_dwordx4 v[18:21], v0, s[24:25] offset:80
	global_load_dwordx4 v[22:25], v0, s[24:25] offset:64
	global_load_dwordx4 v[26:29], v0, s[24:25] offset:144
	global_load_dwordx4 v[30:33], v0, s[24:25] offset:128
	global_load_dwordx4 v[34:37], v0, s[24:25] offset:208
	global_load_dwordx4 v[38:41], v0, s[24:25] offset:192
	global_load_dwordx4 v[42:45], v0, s[24:25] offset:272
	global_load_dwordx4 v[46:49], v0, s[24:25] offset:256
	global_load_dwordx4 v[50:53], v0, s[24:25] offset:336
	global_load_dwordx4 v[54:57], v0, s[24:25] offset:320
	global_load_dwordx4 v[58:61], v0, s[24:25] offset:400
	global_load_dwordx4 v[62:65], v0, s[24:25] offset:384
	global_load_dwordx4 v[66:69], v0, s[24:25] offset:464
	global_load_dwordx4 v[70:73], v0, s[24:25] offset:448
	global_load_dwordx4 v[78:81], v0, s[24:25] offset:528
	global_load_dwordx4 v[86:89], v0, s[24:25] offset:512
	global_load_dwordx4 v[74:77], v0, s[24:25] offset:656
	global_load_dwordx4 v[82:85], v0, s[24:25] offset:640
	global_load_dwordx4 v[10:13], v0, s[24:25] offset:592
	global_load_dwordx4 v[90:93], v0, s[24:25] offset:576
	global_load_dwordx4 v[6:9], v0, s[24:25] offset:720
	global_load_dwordx4 v[94:97], v0, s[24:25] offset:704
	v_bfe_u32 v0, v98, 4, 2
	v_or_b32_e32 v99, s7, v0
	v_lshlrev_b32_e32 v99, 1, v99
	v_bitop3_b32 v0, s7, v98, v0 bitop3:0x36
	v_or_b32_e32 v103, v99, v102
	v_mad_i64_i32 v[100:101], s[10:11], v103, s46, v[100:101]
	v_lshlrev_b32_e32 v0, 4, v0
	v_lshl_add_u64 v[100:101], v[100:101], 0, s[86:87]
	v_and_b32_e32 v0, 0x70, v0
	v_add_u32_e32 v99, s44, v99
	v_lshl_add_u64 v[174:175], v[100:101], 0, v[0:1]
	v_or_b32_e32 v100, v99, v102
	v_ashrrev_i32_e32 v101, 31, v100
	v_lshlrev_b64 v[100:101], 15, v[100:101]
	global_load_lds_dwordx4 v[174:175], off
	v_lshl_add_u64 v[102:103], v[174:175], 0, s[94:95]
	s_add_i32 m0, s0, 0x2000
	v_lshl_add_u64 v[100:101], s[12:13], 0, v[100:101]
	global_load_lds_dwordx4 v[102:103], off
	v_lshl_add_u64 v[102:103], v[174:175], 0, s[96:97]
	s_add_i32 m0, s0, 0x4000
	v_lshl_add_u64 v[180:181], v[100:101], 0, v[0:1]
	global_load_lds_dwordx4 v[102:103], off
	s_add_i32 m0, s0, 0x6000
	v_lshl_add_u64 v[100:101], v[180:181], 0, s[92:93]
	global_load_lds_dwordx4 v[180:181], off
	s_add_i32 m0, s0, 0x8000
	s_mov_b64 s[10:11], 0x30000
	global_load_lds_dwordx4 v[100:101], off
	v_lshl_add_u64 v[100:101], v[174:175], 0, s[10:11]
	s_add_i32 m0, s0, 0xa000
	s_mov_b64 s[10:11], 0x30080
	global_load_lds_dwordx4 v[100:101], off
	v_lshl_add_u64 v[100:101], v[174:175], 0, s[10:11]
	s_add_i32 m0, s0, 0xc000
	s_mov_b64 s[10:11], 0x30100
	global_load_lds_dwordx4 v[100:101], off
	v_lshl_add_u64 v[100:101], v[174:175], 0, s[10:11]
	s_add_i32 m0, s0, 0xe000
	s_mov_b64 s[10:11], 0x200080
	global_load_lds_dwordx4 v[100:101], off
	s_add_i32 m0, s0, 0x10000
	v_lshl_add_u64 v[100:101], v[180:181], 0, s[94:95]
	global_load_lds_dwordx4 v[100:101], off
	v_lshl_add_u64 v[100:101], v[180:181], 0, s[10:11]
	s_add_i32 m0, s0, 0x12000
	ds_bpermute_b32 v211, v231, v209
	global_load_lds_dwordx4 v[100:101], off
	s_waitcnt vmcnt(5)
	s_barrier
	s_cmp_lt_i32 s43, 0
	s_cbranch_scc1 .LBB0_582
	v_lshlrev_b32_e32 v0, 3, v237
	v_lshlrev_b32_e32 v0, 2, v0
	v_and_b32_e32 v222, 63, v98
	global_load_dwordx4 v[98:101], v0, s[26:27] offset:192
	global_load_dwordx4 v[102:105], v0, s[26:27] offset:176
	global_load_dwordx4 v[106:109], v0, s[26:27] offset:240
	global_load_dwordx4 v[110:113], v0, s[26:27] offset:256
	s_waitcnt lgkmcnt(0)
	v_add_f32_e32 v0, v209, v211
	v_fmamk_f32 v0, v0, 0x3baaaaab, v232
	v_cmp_gt_f32_e32 vcc, s5, v0
	v_mul_f32_e32 v176, 0x4b800000, v0
	v_mov_b32_e32 v213, v223
	v_cndmask_b32_e32 v0, v0, v176, vcc
	v_rsq_f32_e32 v0, v0
	s_waitcnt vmcnt(0)
	v_cvt_f32_i32_e32 v223, v239
	v_mov_b32_e32 v221, v201
	v_mov_b32_e32 v227, v205
	v_mul_f32_e32 v176, 0x45800000, v0
	v_cndmask_b32_e32 v0, v0, v176, vcc
	v_mul_f32_e32 v0, 0x3dd53b94, v0
	v_mov_b32_e32 v205, v219
	v_mov_b32_e32 v201, v217
	v_pk_mul_f32 v[216:217], v[0:1], v[220:221] op_sel_hi:[0,1]
	v_mov_b32_e32 v211, v225
	v_mov_b32_e32 v209, v199
	v_mov_b32_e32 v199, v191
	v_mov_b32_e32 v191, v193
	v_mov_b32_e32 v193, v215
	v_pk_mul_f32 v[214:215], v[0:1], v[226:227] op_sel_hi:[0,1]
	s_lshl_b32 s21, s43, 2
	s_ashr_i32 s9, s9, 7
	s_mov_b32 s7, 2
	s_add_i32 s9, s9, s21
	s_add_i32 s21, s21, 4
	s_mov_b32 s28, 0
	s_movk_i32 s86, 0x80
	s_mov_b32 s33, 0
	v_mul_f32_e32 v99, v99, v223
	v_mul_f32_e32 v98, v98, v223
	v_mul_f32_e32 v109, v109, v223
	v_mul_f32_e32 v113, v113, v223
	v_cvt_f64_f32_e32 v[176:177], v113
	v_mul_f64 v[178:179], v[176:177], s[84:85]
	v_rndne_f64_e32 v[178:179], v[178:179]
	v_fma_f64 v[176:177], v[176:177], s[84:85], -v[178:179]
	v_cvt_f32_f64_e32 v113, v[176:177]
	v_mul_f32_e32 v112, v112, v223
	v_cos_f32_e32 v219, v113
	v_sin_f32_e32 v221, v113
	v_cvt_f64_f32_e32 v[112:113], v112
	v_mul_f64 v[176:177], v[112:113], s[84:85]
	v_rndne_f64_e32 v[176:177], v[176:177]
	v_fma_f64 v[112:113], v[112:113], s[84:85], -v[176:177]
	v_cvt_f32_f64_e32 v112, v[112:113]
	v_mul_f32_e32 v111, v111, v223
	v_sin_f32_e32 v220, v112
	v_cos_f32_e32 v218, v112
	v_cvt_f64_f32_e32 v[112:113], v111
	v_mul_f64 v[176:177], v[112:113], s[84:85]
	v_rndne_f64_e32 v[176:177], v[176:177]
	v_mul_f32_e32 v110, v110, v223
	v_fma_f64 v[112:113], v[112:113], s[84:85], -v[176:177]
	v_pk_mul_f32 v[178:179], v[0:1], v[210:211] op_sel_hi:[0,1]
	v_cvt_f64_f32_e32 v[210:211], v110
	v_cvt_f32_f64_e32 v176, v[112:113]
	v_pk_mul_f32 v[112:113], v[0:1], v[212:213] op_sel_hi:[0,1]
	v_mul_f64 v[212:213], v[210:211], s[84:85]
	v_rndne_f64_e32 v[212:213], v[212:213]
	v_fma_f64 v[210:211], v[210:211], s[84:85], -v[212:213]
	v_sin_f32_e32 v111, v176
	v_cos_f32_e32 v177, v176
	v_cvt_f32_f64_e32 v176, v[210:211]
	v_sin_f32_e32 v110, v176
	v_cos_f32_e32 v176, v176
	v_pk_mul_f32 v[6:7], v[6:7], v[178:179]
	v_pk_mul_f32 v[112:113], v[10:11], v[112:113]
	v_mul_f32_e32 v108, v108, v223
	v_pk_mul_f32 v[10:11], v[176:177], v[6:7]
	v_pk_mul_f32 v[6:7], v[110:111], v[6:7]
	v_pk_fma_f32 v[10:11], v[110:111], v[112:113], v[10:11]
	v_cvt_f64_f32_e32 v[110:111], v109
	v_pk_fma_f32 v[6:7], v[176:177], v[112:113], v[6:7] neg_lo:[0,0,1] neg_hi:[0,0,1]
	v_mul_f64 v[112:113], v[110:111], s[84:85]
	v_rndne_f64_e32 v[112:113], v[112:113]
	v_cvt_f64_f32_e32 v[178:179], v108
	v_fma_f64 v[110:111], v[110:111], s[84:85], -v[112:113]
	v_pk_mul_f32 v[112:113], v[0:1], v[206:207] op_sel_hi:[0,1]
	v_mul_f64 v[206:207], v[178:179], s[84:85]
	v_rndne_f64_e32 v[206:207], v[206:207]
	v_cvt_f32_f64_e32 v110, v[110:111]
	v_fma_f64 v[178:179], v[178:179], s[84:85], -v[206:207]
	v_sin_f32_e32 v109, v110
	v_cos_f32_e32 v111, v110
	v_cvt_f32_f64_e32 v110, v[178:179]
	v_sin_f32_e32 v108, v110
	v_cos_f32_e32 v110, v110
	v_pk_mul_f32 v[176:177], v[0:1], v[208:209] op_sel_hi:[0,1]
	v_pk_mul_f32 v[96:97], v[96:97], v[176:177]
	v_pk_mul_f32 v[92:93], v[92:93], v[112:113]
	v_pk_mul_f32 v[112:113], v[110:111], v[96:97]
	v_pk_mul_f32 v[96:97], v[108:109], v[96:97]
	v_pk_fma_f32 v[208:209], v[108:109], v[92:93], v[112:113]
	v_pk_fma_f32 v[206:207], v[110:111], v[92:93], v[96:97] neg_lo:[0,0,1] neg_hi:[0,0,1]
	v_mul_f32_e32 v92, v107, v223
	v_cvt_f64_f32_e32 v[92:93], v92
	v_mul_f64 v[96:97], v[92:93], s[84:85]
	v_rndne_f64_e32 v[96:97], v[96:97]
	v_fma_f64 v[92:93], v[92:93], s[84:85], -v[96:97]
	v_cvt_f32_f64_e32 v92, v[92:93]
	v_sin_f32_e32 v93, v92
	v_cos_f32_e32 v107, v92
	v_mul_f32_e32 v92, v106, v223
	v_cvt_f64_f32_e32 v[110:111], v92
	v_mul_f64 v[112:113], v[110:111], s[84:85]
	v_rndne_f64_e32 v[112:113], v[112:113]
	v_fma_f64 v[110:111], v[110:111], s[84:85], -v[112:113]
	v_cvt_f32_f64_e32 v106, v[110:111]
	v_sin_f32_e32 v92, v106
	v_cos_f32_e32 v106, v106
	v_pk_mul_f32 v[108:109], v[0:1], v[204:205] op_sel_hi:[0,1]
	v_pk_mul_f32 v[96:97], v[0:1], v[202:203] op_sel_hi:[0,1]
	v_pk_mul_f32 v[94:95], v[94:95], v[108:109]
	v_pk_mul_f32 v[90:91], v[90:91], v[96:97]
	v_pk_mul_f32 v[96:97], v[106:107], v[94:95]
	v_cvt_f64_f32_e32 v[178:179], v99
	v_pk_fma_f32 v[204:205], v[92:93], v[90:91], v[96:97]
	v_pk_mul_f32 v[92:93], v[92:93], v[94:95]
	v_mul_f32_e32 v100, v100, v223
	v_pk_fma_f32 v[202:203], v[106:107], v[90:91], v[92:93] neg_lo:[0,0,1] neg_hi:[0,0,1]
	v_mul_f32_e32 v90, v102, v223
	v_cvt_f64_f32_e32 v[90:91], v90
	v_mul_f64 v[92:93], v[90:91], s[84:85]
	v_rndne_f64_e32 v[92:93], v[92:93]
	v_fma_f64 v[90:91], v[90:91], s[84:85], -v[92:93]
	v_cvt_f32_f64_e32 v91, v[90:91]
	v_sin_f32_e32 v90, v91
	v_cos_f32_e32 v94, v91
	v_mul_f32_e32 v91, v103, v223
	v_cvt_f64_f32_e32 v[102:103], v91
	v_mul_f64 v[106:107], v[102:103], s[84:85]
	v_rndne_f64_e32 v[106:107], v[106:107]
	v_fma_f64 v[102:103], v[102:103], s[84:85], -v[106:107]
	v_cvt_f32_f64_e32 v95, v[102:103]
	v_mul_f32_e32 v102, v104, v223
	v_cvt_f64_f32_e32 v[102:103], v102
	v_mul_f64 v[106:107], v[102:103], s[84:85]
	v_rndne_f64_e32 v[106:107], v[106:107]
	v_fma_f64 v[102:103], v[102:103], s[84:85], -v[106:107]
	v_cvt_f32_f64_e32 v103, v[102:103]
	v_sin_f32_e32 v102, v103
	v_cos_f32_e32 v104, v103
	v_mul_f32_e32 v103, v105, v223
	v_cvt_f64_f32_e32 v[110:111], v103
	v_mul_f64 v[112:113], v[110:111], s[84:85]
	v_rndne_f64_e32 v[112:113], v[112:113]
	v_fma_f64 v[110:111], v[110:111], s[84:85], -v[112:113]
	v_pk_mul_f32 v[106:107], v[0:1], v[186:187] op_sel_hi:[0,1]
	v_cvt_f32_f64_e32 v105, v[110:111]
	v_cvt_f64_f32_e32 v[110:111], v98
	v_mul_f64 v[186:187], v[178:179], s[84:85]
	v_mul_f64 v[112:113], v[110:111], s[84:85]
	v_rndne_f64_e32 v[186:187], v[186:187]
	v_sin_f32_e32 v91, v95
	v_cos_f32_e32 v95, v95
	v_rndne_f64_e32 v[112:113], v[112:113]
	v_fma_f64 v[178:179], v[178:179], s[84:85], -v[186:187]
	v_mul_f32_e32 v101, v101, v223
	v_pk_mul_f32 v[108:109], v[0:1], v[190:191] op_sel_hi:[0,1]
	v_fma_f64 v[110:111], v[110:111], s[84:85], -v[112:113]
	v_cvt_f32_f64_e32 v113, v[178:179]
	v_cvt_f64_f32_e32 v[178:179], v100
	v_cvt_f64_f32_e32 v[190:191], v101
	v_pk_mul_f32 v[92:93], v[0:1], v[188:189] op_sel_hi:[0,1]
	v_pk_mul_f32 v[96:97], v[0:1], v[192:193] op_sel_hi:[0,1]
	v_sin_f32_e32 v103, v105
	v_cos_f32_e32 v105, v105
	v_mul_f64 v[186:187], v[178:179], s[84:85]
	v_mul_f64 v[192:193], v[190:191], s[84:85]
	v_cvt_f32_f64_e32 v112, v[110:111]
	v_rndne_f64_e32 v[186:187], v[186:187]
	v_rndne_f64_e32 v[192:193], v[192:193]
	v_pk_mul_f32 v[86:87], v[86:87], v[92:93]
	v_pk_mul_f32 v[92:93], v[82:83], v[96:97]
	v_sin_f32_e32 v98, v112
	v_cos_f32_e32 v112, v112
	v_sin_f32_e32 v99, v113
	v_cos_f32_e32 v113, v113
	v_fma_f64 v[178:179], v[178:179], s[84:85], -v[186:187]
	v_fma_f64 v[190:191], v[190:191], s[84:85], -v[192:193]
	v_pk_mul_f32 v[82:83], v[94:95], v[92:93]
	v_cvt_f32_f64_e32 v186, v[178:179]
	v_cvt_f32_f64_e32 v187, v[190:191]
	v_pk_fma_f32 v[82:83], v[90:91], v[86:87], v[82:83]
	v_pk_mul_f32 v[90:91], v[90:91], v[92:93]
	v_pk_mul_f32 v[84:85], v[84:85], v[108:109]
	v_pk_mul_f32 v[176:177], v[0:1], v[200:201] op_sel_hi:[0,1]
	v_sin_f32_e32 v100, v186
	v_cos_f32_e32 v186, v186
	v_sin_f32_e32 v101, v187
	v_cos_f32_e32 v187, v187
	v_pk_fma_f32 v[86:87], v[94:95], v[86:87], v[90:91] neg_lo:[0,0,1] neg_hi:[0,0,1]
	v_pk_mul_f32 v[88:89], v[88:89], v[106:107]
	v_pk_mul_f32 v[90:91], v[104:105], v[84:85]
	v_pk_mul_f32 v[84:85], v[102:103], v[84:85]
	v_pk_mul_f32 v[110:111], v[0:1], v[196:197] op_sel_hi:[0,1]
	v_pk_fma_f32 v[84:85], v[104:105], v[88:89], v[84:85] neg_lo:[0,0,1] neg_hi:[0,0,1]
	v_pk_mul_f32 v[74:75], v[74:75], v[176:177]
	v_pk_mul_f32 v[188:189], v[0:1], v[198:199] op_sel_hi:[0,1]
	v_cvt_pk_bf16_f32 v86, v86, v87
	v_cvt_pk_bf16_f32 v87, v84, v85
	v_pk_mul_f32 v[78:79], v[78:79], v[110:111]
	v_pk_mul_f32 v[84:85], v[112:113], v[74:75]
	v_pk_mul_f32 v[74:75], v[98:99], v[74:75]
	v_pk_mul_f32 v[178:179], v[0:1], v[194:195] op_sel_hi:[0,1]
	v_pk_fma_f32 v[74:75], v[112:113], v[78:79], v[74:75] neg_lo:[0,0,1] neg_hi:[0,0,1]
	v_pk_mul_f32 v[76:77], v[76:77], v[188:189]
	v_pk_fma_f32 v[90:91], v[102:103], v[88:89], v[90:91]
	v_pk_fma_f32 v[84:85], v[98:99], v[78:79], v[84:85]
	v_cvt_pk_bf16_f32 v88, v74, v75
	v_pk_mul_f32 v[74:75], v[80:81], v[178:179]
	v_pk_mul_f32 v[78:79], v[186:187], v[76:77]
	v_pk_mul_f32 v[76:77], v[100:101], v[76:77]
	v_pk_fma_f32 v[78:79], v[100:101], v[74:75], v[78:79]
	v_pk_fma_f32 v[74:75], v[186:187], v[74:75], v[76:77] neg_lo:[0,0,1] neg_hi:[0,0,1]
	v_cvt_pk_bf16_f32 v82, v82, v83
	v_cvt_pk_bf16_f32 v89, v74, v75
	v_pk_mul_f32 v[74:75], v[0:1], v[170:171] op_sel_hi:[0,1]
	v_pk_mul_f32 v[70:71], v[70:71], v[74:75]
	v_cvt_pk_bf16_f32 v83, v90, v91
	v_cvt_pk_bf16_f32 v90, v70, v71
	v_pk_mul_f32 v[70:71], v[0:1], v[172:173] op_sel_hi:[0,1]
	v_pk_mul_f32 v[70:71], v[72:73], v[70:71]
	v_cvt_pk_bf16_f32 v84, v84, v85
	v_cvt_pk_bf16_f32 v91, v70, v71
	v_pk_mul_f32 v[70:71], v[0:1], v[182:183] op_sel_hi:[0,1]
	v_pk_mul_f32 v[66:67], v[66:67], v[70:71]
	v_cvt_pk_bf16_f32 v85, v78, v79
	v_cvt_pk_bf16_f32 v92, v66, v67
	v_pk_mul_f32 v[66:67], v[0:1], v[184:185] op_sel_hi:[0,1]
	v_pk_mul_f32 v[66:67], v[68:69], v[66:67]
	s_nop 0
	v_cvt_pk_bf16_f32 v93, v66, v67
	v_pk_mul_f32 v[66:67], v[0:1], v[162:163] op_sel_hi:[0,1]
	v_pk_mul_f32 v[62:63], v[62:63], v[66:67]
	s_nop 0
	v_cvt_pk_bf16_f32 v94, v62, v63
	v_pk_mul_f32 v[62:63], v[0:1], v[166:167] op_sel_hi:[0,1]
	v_pk_mul_f32 v[62:63], v[64:65], v[62:63]
	s_nop 0
	v_cvt_pk_bf16_f32 v95, v62, v63
	v_pk_mul_f32 v[62:63], v[0:1], v[164:165] op_sel_hi:[0,1]
	v_pk_mul_f32 v[58:59], v[58:59], v[62:63]
	s_nop 0
	v_cvt_pk_bf16_f32 v96, v58, v59
	v_pk_mul_f32 v[58:59], v[0:1], v[168:169] op_sel_hi:[0,1]
	v_pk_mul_f32 v[58:59], v[60:61], v[58:59]
	s_nop 0
	v_cvt_pk_bf16_f32 v97, v58, v59
	v_pk_mul_f32 v[58:59], v[0:1], v[154:155] op_sel_hi:[0,1]
	v_pk_mul_f32 v[54:55], v[54:55], v[58:59]
	s_nop 0
	v_cvt_pk_bf16_f32 v98, v54, v55
	v_pk_mul_f32 v[54:55], v[0:1], v[160:161] op_sel_hi:[0,1]
	v_pk_mul_f32 v[54:55], v[56:57], v[54:55]
	s_nop 0
	v_cvt_pk_bf16_f32 v99, v54, v55
	v_pk_mul_f32 v[54:55], v[0:1], v[158:159] op_sel_hi:[0,1]
	v_pk_mul_f32 v[50:51], v[50:51], v[54:55]
	s_nop 0
	v_cvt_pk_bf16_f32 v100, v50, v51
	v_pk_mul_f32 v[50:51], v[0:1], v[156:157] op_sel_hi:[0,1]
	v_pk_mul_f32 v[50:51], v[52:53], v[50:51]
	s_nop 0
	v_cvt_pk_bf16_f32 v101, v50, v51
	v_pk_mul_f32 v[50:51], v[0:1], v[146:147] op_sel_hi:[0,1]
	v_pk_mul_f32 v[46:47], v[46:47], v[50:51]
	v_mov_b32_e32 v50, 0
	v_cvt_pk_bf16_f32 v102, v46, v47
	v_pk_mul_f32 v[46:47], v[0:1], v[148:149] op_sel_hi:[0,1]
	v_pk_mul_f32 v[46:47], v[48:49], v[46:47]
	s_nop 0
	v_cvt_pk_bf16_f32 v103, v46, v47
	v_pk_mul_f32 v[46:47], v[0:1], v[150:151] op_sel_hi:[0,1]
	v_pk_mul_f32 v[42:43], v[42:43], v[46:47]
	s_nop 0
	v_cvt_pk_bf16_f32 v104, v42, v43
	v_pk_mul_f32 v[42:43], v[0:1], v[152:153] op_sel_hi:[0,1]
	v_pk_mul_f32 v[42:43], v[44:45], v[42:43]
	s_nop 0
	v_cvt_pk_bf16_f32 v105, v42, v43
	v_pk_mul_f32 v[42:43], v[0:1], v[138:139] op_sel_hi:[0,1]
	v_pk_mul_f32 v[38:39], v[38:39], v[42:43]
	s_nop 0
	v_cvt_pk_bf16_f32 v106, v38, v39
	v_pk_mul_f32 v[38:39], v[0:1], v[140:141] op_sel_hi:[0,1]
	v_pk_mul_f32 v[38:39], v[40:41], v[38:39]
	s_nop 0
	v_cvt_pk_bf16_f32 v107, v38, v39
	v_pk_mul_f32 v[38:39], v[0:1], v[142:143] op_sel_hi:[0,1]
	v_pk_mul_f32 v[34:35], v[34:35], v[38:39]
	s_nop 0
	v_cvt_pk_bf16_f32 v108, v34, v35
	v_pk_mul_f32 v[34:35], v[0:1], v[144:145] op_sel_hi:[0,1]
	v_pk_mul_f32 v[34:35], v[36:37], v[34:35]
	s_nop 0
	v_cvt_pk_bf16_f32 v109, v34, v35
	v_pk_mul_f32 v[34:35], v[0:1], v[130:131] op_sel_hi:[0,1]
	v_pk_mul_f32 v[30:31], v[30:31], v[34:35]
	v_mov_b32_e32 v34, 0
	v_cvt_pk_bf16_f32 v110, v30, v31
	v_pk_mul_f32 v[30:31], v[0:1], v[132:133] op_sel_hi:[0,1]
	v_pk_mul_f32 v[30:31], v[32:33], v[30:31]
	s_nop 0
	v_cvt_pk_bf16_f32 v111, v30, v31
	v_pk_mul_f32 v[30:31], v[0:1], v[134:135] op_sel_hi:[0,1]
	v_pk_mul_f32 v[26:27], v[26:27], v[30:31]
	s_nop 0
	v_cvt_pk_bf16_f32 v112, v26, v27
	v_pk_mul_f32 v[26:27], v[0:1], v[136:137] op_sel_hi:[0,1]
	v_pk_mul_f32 v[26:27], v[28:29], v[26:27]
	s_nop 0
	v_cvt_pk_bf16_f32 v113, v26, v27
	v_pk_mul_f32 v[26:27], v[0:1], v[114:115] op_sel_hi:[0,1]
	v_pk_mul_f32 v[22:23], v[22:23], v[26:27]
	s_nop 0
	v_cvt_pk_bf16_f32 v114, v22, v23
	v_pk_mul_f32 v[22:23], v[0:1], v[116:117] op_sel_hi:[0,1]
	v_pk_mul_f32 v[22:23], v[24:25], v[22:23]
	s_nop 0
	v_cvt_pk_bf16_f32 v115, v22, v23
	v_pk_mul_f32 v[22:23], v[0:1], v[126:127] op_sel_hi:[0,1]
	v_pk_mul_f32 v[18:19], v[18:19], v[22:23]
	v_cvt_pk_bf16_f32 v126, v202, v203
	v_cvt_pk_bf16_f32 v116, v18, v19
	v_pk_mul_f32 v[18:19], v[0:1], v[128:129] op_sel_hi:[0,1]
	v_pk_mul_f32 v[18:19], v[20:21], v[18:19]
	v_cvt_pk_bf16_f32 v128, v6, v7
	v_cvt_pk_bf16_f32 v117, v18, v19
	v_pk_mul_f32 v[18:19], v[0:1], v[118:119] op_sel_hi:[0,1]
	v_pk_mul_f32 v[14:15], v[14:15], v[18:19]
	v_cvt_pk_bf16_f32 v127, v206, v207
	v_cvt_pk_bf16_f32 v118, v14, v15
	v_pk_mul_f32 v[14:15], v[0:1], v[120:121] op_sel_hi:[0,1]
	v_pk_mul_f32 v[14:15], v[16:17], v[14:15]
	v_mov_b32_e32 v18, 0
	v_cvt_pk_bf16_f32 v119, v14, v15
	v_pk_mul_f32 v[14:15], v[0:1], v[122:123] op_sel_hi:[0,1]
	v_pk_mul_f32 v[2:3], v[2:3], v[14:15]
	v_cvt_pk_bf16_f32 v122, v204, v205
	v_cvt_pk_bf16_f32 v120, v2, v3
	v_pk_mul_f32 v[2:3], v[0:1], v[124:125] op_sel_hi:[0,1]
	v_pk_mul_f32 v[2:3], v[4:5], v[2:3]
	v_pk_mul_f32 v[4:5], v[8:9], v[214:215]
	v_cvt_pk_bf16_f32 v121, v2, v3
	v_pk_mul_f32 v[2:3], v[12:13], v[216:217]
	v_pk_mul_f32 v[6:7], v[218:219], v[4:5]
	v_pk_mul_f32 v[4:5], v[220:221], v[4:5]
	v_pk_fma_f32 v[6:7], v[220:221], v[2:3], v[6:7]
	v_pk_fma_f32 v[2:3], v[218:219], v[2:3], v[4:5] neg_lo:[0,0,1] neg_hi:[0,0,1]
	v_mov_b32_e32 v0, 0
	v_cvt_pk_bf16_f32 v123, v208, v209
	v_cvt_pk_bf16_f32 v124, v10, v11
	v_cvt_pk_bf16_f32 v125, v6, v7
	v_cvt_pk_bf16_f32 v129, v2, v3
	v_mov_b32_e32 v2, 0
	v_mov_b32_e32 v3, v0
	v_mov_b32_e32 v4, v0
	v_mov_b32_e32 v5, v0
	v_mov_b32_e32 v6, v0
	v_mov_b32_e32 v7, v0
	v_mov_b32_e32 v8, v0
	v_mov_b32_e32 v9, v0
	v_mov_b32_e32 v10, v0
	v_mov_b32_e32 v11, v0
	v_mov_b32_e32 v12, v0
	v_mov_b32_e32 v13, v0
	v_mov_b32_e32 v14, v0
	v_mov_b32_e32 v15, v0
	v_mov_b32_e32 v16, v0
	v_mov_b32_e32 v17, v0
	v_mov_b32_e32 v19, v0
	v_mov_b32_e32 v20, v0
	v_mov_b32_e32 v21, v0
	v_mov_b32_e32 v22, v0
	v_mov_b32_e32 v23, v0
	v_mov_b32_e32 v24, v0
	v_mov_b32_e32 v25, v0
	v_mov_b32_e32 v26, v0
	v_mov_b32_e32 v27, v0
	v_mov_b32_e32 v28, v0
	v_mov_b32_e32 v29, v0
	v_mov_b32_e32 v30, v0
	v_mov_b32_e32 v31, v0
	v_mov_b32_e32 v32, v0
	v_mov_b32_e32 v33, v0
	v_mov_b32_e32 v35, v0
	v_mov_b32_e32 v36, v0
	v_mov_b32_e32 v37, v0
	v_mov_b32_e32 v38, v0
	v_mov_b32_e32 v39, v0
	v_mov_b32_e32 v40, v0
	v_mov_b32_e32 v41, v0
	v_mov_b32_e32 v42, v0
	v_mov_b32_e32 v43, v0
	v_mov_b32_e32 v44, v0
	v_mov_b32_e32 v45, v0
	v_mov_b32_e32 v46, v0
	v_mov_b32_e32 v47, v0
	v_mov_b32_e32 v48, v0
	v_mov_b32_e32 v49, v0
	v_mov_b32_e32 v51, v0
	v_mov_b32_e32 v52, v0
	v_mov_b32_e32 v53, v0
	v_mov_b32_e32 v54, v0
	v_mov_b32_e32 v55, v0
	v_mov_b32_e32 v56, v0
	v_mov_b32_e32 v57, v0
	v_mov_b32_e32 v58, v0
	v_mov_b32_e32 v59, v0
	v_mov_b32_e32 v60, v0
	v_mov_b32_e32 v61, v0
	v_mov_b32_e32 v62, v0
	v_mov_b32_e32 v63, v0
	v_mov_b32_e32 v64, v0
	v_mov_b32_e32 v65, v0
	v_mov_b32_e32 v208, v222
	v_lshlrev_b32_e32 v211, 3, v208
	v_lshrrev_b32_e32 v209, 1, v208
	v_lshlrev_b32_e32 v210, 7, v208
	v_and_b32_e32 v211, 8, v211
	v_ashrrev_i32_e32 v208, 5, v208
	v_add_u32_e32 v208, v211, v208
	v_and_b32_e32 v210, 0xf00, v210
	v_bitop3_b32 v211, v208, v209, 7 bitop3:0x78
	v_add_u32_e32 v212, 2, v208
	v_add_u32_e32 v213, 4, v208
	v_add_u32_e32 v208, 6, v208
	v_bitop3_b32 v212, v212, v209, 7 bitop3:0x78
	v_bitop3_b32 v213, v213, v209, 7 bitop3:0x78
	v_bitop3_b32 v208, v208, v209, 7 bitop3:0x78
	v_lshl_add_u32 v218, v211, 4, v210
	v_lshl_add_u32 v219, v212, 4, v210
	v_lshl_add_u32 v209, v213, 4, v210
	v_lshl_add_u32 v208, v208, 4, v210
	s_branch .LBB0_574
	s_nop 0
